# GEMM tile setup: first (96-instruction) redundant accumulator zeroing block also moved to a cold stub
# speedup vs baseline: 1.0110x; 1.0033x over previous
.LBB0_226:
	s_andn2_b64 vcc, exec, s[46:47]
	s_cbranch_vccnz .Lgemm_zero_stub2
	s_lshl_b64 s[36:37], s[40:41], 1
	v_readlane_b32 s12, v250, 45
	s_add_u32 s86, s12, s36
	v_readlane_b32 s15, v250, 46
	s_addc_u32 s87, s15, s37
	s_add_i32 s49, s0, 0x100
	s_add_i32 s21, s49, 0x10000
	s_add_u32 s58, s86, s94
	s_addc_u32 s59, s87, s95
	s_add_i32 s75, s49, 0x12000
	s_lshl_b64 s[0:1], s[34:35], 1
	v_readlane_b32 s13, v250, 43
	s_add_u32 s92, s13, s0
	v_readlane_b32 s10, v250, 44
	s_addc_u32 s93, s10, s1
	s_add_u32 s64, s92, s94
	s_addc_u32 s65, s93, s95
	s_add_i32 s34, s14, 0x80
	s_mul_hi_i32 s1, s34, s18
	s_mul_i32 s0, s34, s18
	s_add_i32 s84, s49, 0x2000
	s_lshl_b64 s[0:1], s[0:1], 1
	s_add_u32 s46, s12, s0
	s_addc_u32 s47, s15, s1
	s_add_i32 s85, s49, 0x14000
	s_add_u32 vcc_lo, s46, s94
	s_mov_b32 m0, s21
	s_addc_u32 vcc_hi, s47, s95
	s_add_i32 s40, s42, 0x80
	global_load_lds_dwordx4 v170, s[86:87]
	s_mov_b32 m0, s75
	s_mul_hi_i32 s1, s40, s18
	s_mul_i32 s0, s40, s18
	global_load_lds_dwordx4 v170, s[58:59]
	s_mov_b32 m0, s49
	s_add_i32 s54, s49, 0x16000
	s_lshl_b64 s[0:1], s[0:1], 1
	global_load_lds_dwordx4 v170, s[92:93]
	s_mov_b32 m0, s84
	s_add_u32 s68, s13, s0
	global_load_lds_dwordx4 v170, s[64:65]
	s_mov_b32 m0, s85
	s_addc_u32 s69, s10, s1
	s_add_i32 s55, s49, 0x4000
	global_load_lds_dwordx4 v170, s[46:47]
	s_mov_b32 m0, s54
	s_add_u32 s36, s68, s94
	global_load_lds_dwordx4 v170, vcc
	s_mov_b32 m0, s55
	s_addc_u32 s37, s69, s95
	s_add_i32 s0, s49, 0x6000
	global_load_lds_dwordx4 v170, s[68:69]
	s_mov_b32 m0, s0
	s_cmp_lg_u32 s57, 1
	global_load_lds_dwordx4 v170, s[36:37]
	s_cbranch_scc1 .LBB0_229
	s_barrier

.Lgemm_zero_stub2:
	v_mov_b32_e32 v123, 0
	v_mov_b32_e32 v122, 0
	v_mov_b32_e32 v121, 0
	v_mov_b32_e32 v120, 0
	v_mov_b32_e32 v127, 0
	v_mov_b32_e32 v126, 0
	v_mov_b32_e32 v125, 0
	v_mov_b32_e32 v124, 0
	v_mov_b32_e32 v115, 0
	v_mov_b32_e32 v114, 0
	v_mov_b32_e32 v113, 0
	v_mov_b32_e32 v112, 0
	v_mov_b32_e32 v119, 0
	v_mov_b32_e32 v118, 0
	v_mov_b32_e32 v117, 0
	v_mov_b32_e32 v116, 0
	v_mov_b32_e32 v107, 0
	v_mov_b32_e32 v106, 0
	v_mov_b32_e32 v105, 0
	v_mov_b32_e32 v104, 0
	v_mov_b32_e32 v111, 0
	v_mov_b32_e32 v110, 0
	v_mov_b32_e32 v109, 0
	v_mov_b32_e32 v108, 0
	v_mov_b32_e32 v83, 0
	v_mov_b32_e32 v82, 0
	v_mov_b32_e32 v81, 0
	v_mov_b32_e32 v80, 0
	v_mov_b32_e32 v87, 0
	v_mov_b32_e32 v86, 0
	v_mov_b32_e32 v85, 0
	v_mov_b32_e32 v84, 0
	v_mov_b32_e32 v71, 0
	v_mov_b32_e32 v70, 0
	v_mov_b32_e32 v69, 0
	v_mov_b32_e32 v68, 0
	v_mov_b32_e32 v79, 0
	v_mov_b32_e32 v78, 0
	v_mov_b32_e32 v77, 0
	v_mov_b32_e32 v76, 0
	v_mov_b32_e32 v55, 0
	v_mov_b32_e32 v54, 0
	v_mov_b32_e32 v53, 0
	v_mov_b32_e32 v52, 0
	v_mov_b32_e32 v63, 0
	v_mov_b32_e32 v62, 0
	v_mov_b32_e32 v61, 0
	v_mov_b32_e32 v60, 0
	v_mov_b32_e32 v43, 0
	v_mov_b32_e32 v42, 0
	v_mov_b32_e32 v41, 0
	v_mov_b32_e32 v40, 0
	v_mov_b32_e32 v47, 0
	v_mov_b32_e32 v46, 0
	v_mov_b32_e32 v45, 0
	v_mov_b32_e32 v44, 0
	v_mov_b32_e32 v31, 0
	v_mov_b32_e32 v30, 0
	v_mov_b32_e32 v29, 0
	v_mov_b32_e32 v28, 0
	v_mov_b32_e32 v35, 0
	v_mov_b32_e32 v34, 0
	v_mov_b32_e32 v33, 0
	v_mov_b32_e32 v32, 0
	v_mov_b32_e32 v99, 0
	v_mov_b32_e32 v98, 0
	v_mov_b32_e32 v97, 0
	v_mov_b32_e32 v96, 0
	v_mov_b32_e32 v103, 0
	v_mov_b32_e32 v102, 0
	v_mov_b32_e32 v101, 0
	v_mov_b32_e32 v100, 0
	v_mov_b32_e32 v91, 0
	v_mov_b32_e32 v90, 0
	v_mov_b32_e32 v89, 0
	v_mov_b32_e32 v88, 0
	v_mov_b32_e32 v95, 0
	v_mov_b32_e32 v94, 0
	v_mov_b32_e32 v93, 0
	v_mov_b32_e32 v92, 0
	v_mov_b32_e32 v67, 0
	v_mov_b32_e32 v66, 0
	v_mov_b32_e32 v65, 0
	v_mov_b32_e32 v64, 0
	v_mov_b32_e32 v75, 0
	v_mov_b32_e32 v74, 0
	v_mov_b32_e32 v73, 0
	v_mov_b32_e32 v72, 0
	v_mov_b32_e32 v51, 0
	v_mov_b32_e32 v50, 0
	v_mov_b32_e32 v49, 0
	v_mov_b32_e32 v48, 0
	v_mov_b32_e32 v59, 0
	v_mov_b32_e32 v58, 0
	v_mov_b32_e32 v57, 0
	v_mov_b32_e32 v56, 0
	s_branch .LBB0_239
	s_nop 0
	s_nop 0
	s_nop 0
	s_nop 0
	s_nop 0
	s_nop 0
	s_nop 0
	s_nop 0
	s_nop 0
	s_nop 0
	s_nop 0
	s_nop 0
	s_nop 0
	s_nop 0
	s_nop 0
	s_nop 0
	s_nop 0
	s_nop 0
	s_nop 0
	s_nop 0
	s_nop 0
	s_nop 0
	s_nop 0
	s_nop 0
	s_nop 0
	s_nop 0
	s_nop 0
	s_nop 0
	s_nop 0
	s_nop 0
	s_nop 0
	s_nop 0
	s_nop 0
	s_nop 0
	s_nop 0
	s_nop 0
	s_nop 0
	s_nop 0
	s_nop 0
	s_nop 0
	s_nop 0
	s_nop 0
	s_nop 0
	s_nop 0
	s_nop 0
	s_nop 0
	s_nop 0
	s_nop 0
	s_nop 0
	s_nop 0
	s_nop 0
	s_nop 0
	s_nop 0
	s_nop 0
	s_nop 0
	s_nop 0
	s_nop 0
	s_nop 0
	s_nop 0
	s_nop 0
	s_nop 0
	s_nop 0
